# v27 + stick-breaking body: redundant s_nop and NaN-canonicalising self-max removed (trans wait states re-derived)
# speedup vs baseline: 1.0231x; 1.0055x over previous
; __device__ __forceinline__ float exp2_(float x) { return __builtin_amdgcn_exp2f(x); }
; __device__ __forceinline__ float log2_(float x) { return __builtin_amdgcn_logf(x); }
; __device__ __forceinline__ float swap_partner(float x, int hh) { auto rr = __builtin_amdgcn_permlane32_swap(__float_as_uint(x), __float_as_uint(x), false, false); return __uint_as_float(hh ? rr[0] : rr[1]); }
; __device__ __forceinline__ float exp2_negabs(float x) { float r; asm("v_exp_f32 %0, -|%1|\n\ts_nop 1" : "=v"(r) : "v"(x)); return r; }
; __device__ __forceinline__ void sb_sub(f32x16& s, float& carry, const int hh) {
;     float w[16];
; #pragma unroll
;     for (int i = 0; i < 16; ++i) { const float z = s[i]; const float t = log2_(1.f + exp2_negabs(z));
;         w[i] = -(__builtin_fmaxf(z, 0.f) + t); }
;     const float GA = ((w[0] + w[1]) + (w[2] + w[3])) + ((w[4] + w[5]) + (w[6] + w[7])), GB = ((w[8] + w[9]) + (w[10] + w[11])) + ((w[12] + w[13]) + (w[14] + w[15]));
;     const float GAp = swap_partner(GA, hh), GBp = swap_partner(GB, hh);
;     float a = carry + (hh == 0 ? GBp : 0.f);
; #pragma unroll
;     for (int i = 15; i >= 8; --i) { const float wi = w[i]; s[i] = exp2_((s[i] + wi) + a); a += wi; }
;     a = carry + GB + GBp + (hh == 0 ? GAp : 0.f);
; #pragma unroll
;     for (int i = 7; i >= 0; --i) { const float wi = w[i]; s[i] = exp2_((s[i] + wi) + a); a += wi; }
.LBB0_1109:
	v_max_f32_e32 v159, 0, v98
	v_exp_f32 v157, -|v99|
	s_nop 0
	v_add_f32_e32 v157, 1.0, v157
	v_log_f32_e32 v161, v157
	v_max_f32_e32 v177, 0, v99
	v_exp_f32 v157, -|v100|
	v_max_f32_e32 v158, 0, v96
	v_add_f32_e32 v157, 1.0, v157
	v_log_f32_e32 v178, v157
	v_max_f32_e32 v180, 0, v100
	v_exp_f32 v157, -|v101|
	v_exp_f32 v15, -|v97|
	v_exp_f32 v14, -|v96|
	s_nop 0
	v_add_f32_e32 v157, 1.0, v157
	v_log_f32_e32 v190, v157
	v_max_f32_e32 v192, 0, v101
	v_exp_f32 v157, -|v102|
	v_add_f32_e32 v15, 1.0, v15
	v_add_f32_e32 v157, 1.0, v157
	v_log_f32_e32 v179, v157
	v_max_f32_e32 v181, 0, v102
	v_exp_f32 v157, -|v103|
	v_log_f32_e32 v160, v15
	v_add_f32_e32 v157, 1.0, v157
	v_log_f32_e32 v191, v157
	v_max_f32_e32 v193, 0, v103
	v_exp_f32 v157, -|v104|
	s_nop 0
	v_add_f32_e32 v157, 1.0, v157
	v_log_f32_e32 v194, v157
	v_max_f32_e32 v196, 0, v104
	v_exp_f32 v157, -|v105|
	v_max_f32_e32 v176, 0, v97
	v_add_f32_e32 v157, 1.0, v157
	v_log_f32_e32 v198, v157
	v_max_f32_e32 v200, 0, v105
	v_exp_f32 v157, -|v106|
	v_exp_f32 v15, -|v98|
	v_add_f32_e32 v14, 1.0, v14
	v_add_f32_e32 v157, 1.0, v157
	v_log_f32_e32 v195, v157
	v_max_f32_e32 v197, 0, v106
	v_exp_f32 v157, -|v107|
	v_add_f32_e32 v15, 1.0, v15
	v_add_f32_e32 v157, 1.0, v157
	v_log_f32_e32 v199, v157
	v_max_f32_e32 v201, 0, v107
	v_exp_f32 v157, -|v108|
	v_log_f32_e32 v14, v14
	v_add_f32_e32 v157, 1.0, v157
	v_log_f32_e32 v202, v157
	v_max_f32_e32 v204, 0, v108
	v_exp_f32 v157, -|v109|
	v_log_f32_e32 v15, v15
	v_add_f32_e32 v157, 1.0, v157
	v_log_f32_e32 v206, v157
	v_max_f32_e32 v214, 0, v109
	v_exp_f32 v157, -|v110|
	v_pk_add_f32 v[14:15], v[158:159], v[14:15]
	v_add_f32_e32 v157, 1.0, v157
	v_log_f32_e32 v203, v157
	v_max_f32_e32 v205, 0, v110
	v_exp_f32 v157, -|v111|
	v_pk_add_f32 v[158:159], v[176:177], v[160:161]
	v_add_f32_e32 v157, 1.0, v157
	v_log_f32_e32 v207, v157
	v_pk_add_f32 v[176:177], v[192:193], v[190:191]
	v_sub_f32_e32 v225, v103, v177
	v_exp_f32 v103, -|v80|
	v_max_f32_e32 v215, 0, v111
	v_add_f32_e32 v103, 1.0, v103
	v_pk_add_f32 v[192:193], v[196:197], v[194:195]
	v_pk_add_f32 v[194:195], v[200:201], v[198:199]
	v_pk_add_f32 v[198:199], v[204:205], v[202:203]
	v_log_f32_e32 v204, v103
	v_pk_add_f32 v[200:201], v[214:215], v[206:207]
	v_max_f32_e32 v206, 0, v80
	v_exp_f32 v103, -|v81|
	v_pk_add_f32 v[160:161], v[180:181], v[178:179]
	v_add_f32_e32 v103, 1.0, v103
	v_log_f32_e32 v205, v103
	v_max_f32_e32 v207, 0, v81
	v_exp_f32 v103, -|v82|
	v_pk_add_f32 v[196:197], v[194:195], v[192:193] neg_lo:[1,1] neg_hi:[1,1]
	v_add_f32_e32 v103, 1.0, v103
	v_log_f32_e32 v214, v103
	v_max_f32_e32 v228, 0, v82
	v_exp_f32 v103, -|v83|
	v_pk_add_f32 v[202:203], v[200:201], v[198:199] neg_lo:[1,1] neg_hi:[1,1]
	v_add_f32_e32 v103, 1.0, v103
	v_log_f32_e32 v215, v103
	v_max_f32_e32 v229, 0, v83
	v_exp_f32 v103, -|v84|
	v_pk_add_f32 v[196:197], v[196:197], v[196:197] op_sel:[0,1] op_sel_hi:[1,0]
	v_add_f32_e32 v103, 1.0, v103
	v_log_f32_e32 v230, v103
	v_max_f32_e32 v232, 0, v84
	v_exp_f32 v103, -|v85|
	v_pk_add_f32 v[202:203], v[202:203], v[202:203] op_sel:[0,1] op_sel_hi:[1,0]
	v_add_f32_e32 v103, 1.0, v103
	v_log_f32_e32 v231, v103
	v_max_f32_e32 v233, 0, v85
	v_exp_f32 v103, -|v86|
	v_pk_add_f32 v[230:231], v[232:233], v[230:231]
	v_add_f32_e32 v103, 1.0, v103
	v_log_f32_e32 v234, v103
	v_max_f32_e32 v236, 0, v86
	v_exp_f32 v103, -|v87|
	v_sub_f32_e64 v197, -v231, v230
	v_add_f32_e32 v103, 1.0, v103
	v_log_f32_e32 v235, v103
	v_max_f32_e32 v237, 0, v87
	v_exp_f32 v103, -|v88|
	v_pk_add_f32 v[234:235], v[236:237], v[234:235]
	v_add_f32_e32 v103, 1.0, v103
	v_log_f32_e32 v178, v103
	v_max_f32_e32 v180, 0, v88
	v_exp_f32 v103, -|v89|
	v_sub_f32_e64 v203, -v235, v234
	v_add_f32_e32 v103, 1.0, v103
	v_log_f32_e32 v238, v103
	v_max_f32_e32 v240, 0, v89
	v_exp_f32 v103, -|v90|
	v_pk_add_f32 v[196:197], v[196:197], v[202:203]
	v_add_f32_e32 v103, 1.0, v103
	v_log_f32_e32 v179, v103
	v_max_f32_e32 v181, 0, v90
	v_exp_f32 v103, -|v91|
	v_pk_add_f32 v[178:179], v[180:181], v[178:179]
	v_add_f32_e32 v103, 1.0, v103
	v_log_f32_e32 v239, v103
	v_max_f32_e32 v241, 0, v91
	v_exp_f32 v103, -|v92|
	v_pk_add_f32 v[180:181], v[240:241], v[238:239]
	v_add_f32_e32 v103, 1.0, v103
	v_log_f32_e32 v242, v103
	v_max_f32_e32 v244, 0, v92
	v_exp_f32 v103, -|v93|
	v_sub_f32_e32 v236, v87, v235
	v_add_f32_e32 v103, 1.0, v103
	v_log_f32_e32 v246, v103
	v_max_f32_e32 v248, 0, v93
	v_exp_f32 v103, -|v94|
	v_mov_b32_e32 v87, v196
	v_add_f32_e32 v103, 1.0, v103
	v_log_f32_e32 v243, v103
	v_max_f32_e32 v245, 0, v94
	v_exp_f32 v103, -|v95|
	v_pk_add_f32 v[240:241], v[244:245], v[242:243]
	v_add_f32_e32 v103, 1.0, v103
	v_log_f32_e32 v247, v103
	v_max_f32_e32 v249, 0, v95
	v_sub_f32_e32 v157, v111, v201
	v_pk_add_f32 v[242:243], v[248:249], v[246:247]
	v_mov_b32_e32 v202, v199
	v_pk_add_f32 v[244:245], v[242:243], v[240:241] neg_lo:[1,1] neg_hi:[1,1]
	v_sub_f32_e32 v252, v95, v243
	v_mov_b32_e32 v95, v196
	v_pk_add_f32 v[244:245], v[244:245], v[244:245] op_sel_hi:[0,1]
	s_nop 0
	v_permlane32_swap_b32_e32 v87, v95
	v_cndmask_b32_e64 v244, v87, v95, s[8:9]
	v_cndmask_b32_e64 v87, 0, v244, s[8:9]
	v_add_f32_e32 v111, v156, v87
	v_mov_b32_e32 v203, v201
	v_add_f32_e32 v87, v157, v111
	v_pk_add_f32 v[110:111], v[110:111], v[202:203] neg_lo:[0,1] neg_hi:[0,1]
	v_exp_f32_e32 v232, v87
	v_add_f32_e32 v87, v110, v111
	v_mov_b32_e32 v110, v109
	v_mov_b32_e32 v201, v199
	v_pk_add_f32 v[110:111], v[110:111], v[200:201] neg_lo:[0,1] neg_hi:[0,1]
	v_exp_f32_e32 v202, v87
	v_add_f32_e32 v87, v110, v111
	v_mov_b32_e32 v109, v111
	v_mov_b32_e32 v110, v198
	v_mov_b32_e32 v111, v200
	v_pk_add_f32 v[108:109], v[108:109], v[110:111] neg_lo:[0,1] neg_hi:[0,1]
; __device__ __forceinline__ float exp2_(float x) { return __builtin_amdgcn_exp2f(x); }
; __device__ __forceinline__ float swap_partner(float x, int hh) { auto rr = __builtin_amdgcn_permlane32_swap(__float_as_uint(x), __float_as_uint(x), false, false); return __uint_as_float(hh ? rr[0] : rr[1]); }
; __device__ __forceinline__ void sb_sub(f32x16& s, float& carry, const int hh) {
;     ...
;     const float GAp = swap_partner(GA, hh), GBp = swap_partner(GB, hh);
;     float a = carry + (hh == 0 ? GBp : 0.f);
; #pragma unroll
;     for (int i = 15; i >= 8; --i) { const float wi = w[i]; s[i] = exp2_((s[i] + wi) + a); a += wi; }
;     a = carry + GB + GBp + (hh == 0 ? GAp : 0.f);
; #pragma unroll
;     for (int i = 7; i >= 0; --i) { const float wi = w[i]; s[i] = exp2_((s[i] + wi) + a); a += wi; }
;     carry += (GA + GB) + (GAp + GBp);
	v_exp_f32_e32 v201, v87
	v_add_f32_e32 v87, v108, v109
	v_mov_b32_e32 v108, v107
	v_pk_mov_b32 v[110:111], v[194:195], v[198:199] op_sel:[1,0]
	v_exp_f32_e32 v200, v87
	v_pk_add_f32 v[108:109], v[108:109], v[110:111] neg_lo:[0,1] neg_hi:[0,1]
	v_pk_add_f32 v[226:227], v[158:159], v[14:15] neg_lo:[1,1] neg_hi:[1,1]
	v_add_f32_e32 v87, v108, v109
	v_mov_b32_e32 v107, v109
	v_mov_b32_e32 v108, v193
	v_mov_b32_e32 v109, v195
	v_pk_add_f32 v[106:107], v[106:107], v[108:109] neg_lo:[0,1] neg_hi:[0,1]
	v_exp_f32_e32 v198, v87
	v_add_f32_e32 v87, v106, v107
	v_mov_b32_e32 v106, v105
	v_mov_b32_e32 v195, v193
	v_pk_add_f32 v[190:191], v[176:177], v[160:161] neg_lo:[1,1] neg_hi:[1,1]
	v_pk_add_f32 v[106:107], v[106:107], v[194:195] neg_lo:[0,1] neg_hi:[0,1]
	v_pk_add_f32 v[226:227], v[226:227], v[226:227] op_sel:[0,1] op_sel_hi:[1,0]
	v_pk_add_f32 v[190:191], v[190:191], v[190:191] op_sel:[0,1] op_sel_hi:[1,0]
	v_exp_f32_e32 v199, v87
	v_add_f32_e32 v87, v106, v107
	v_mov_b32_e32 v105, v107
	v_pk_add_f32 v[106:107], v[228:229], v[214:215]
	v_pk_add_f32 v[110:111], v[206:207], v[204:205]
	v_sub_f32_e64 v191, -v107, v106
	v_sub_f32_e64 v227, -v111, v110
	v_mov_b32_e32 v193, v194
	v_pk_add_f32 v[190:191], v[226:227], v[190:191]
	v_pk_add_f32 v[238:239], v[180:181], v[178:179] neg_lo:[1,1] neg_hi:[1,1]
	v_pk_add_f32 v[104:105], v[104:105], v[192:193] neg_lo:[0,1] neg_hi:[0,1]
	v_mov_b32_e32 v95, v190
	v_mov_b32_e32 v103, v190
	v_pk_add_f32 v[238:239], v[238:239], v[238:239] op_sel_hi:[0,1]
	v_exp_f32_e32 v195, v87
	v_add_f32_e32 v87, v104, v105
	v_permlane32_swap_b32_e32 v95, v103
	v_exp_f32_e32 v194, v87
	v_add_f32_e32 v87, v156, v196
	v_cndmask_b32_e64 v238, v95, v103, s[8:9]
	v_add_f32_e32 v87, v87, v244
	v_cndmask_b32_e64 v95, 0, v238, s[8:9]
	v_add_f32_e32 v103, v95, v87
	v_mov_b32_e32 v192, v161
	v_mov_b32_e32 v193, v177
	v_add_f32_e32 v87, v225, v103
	v_pk_add_f32 v[102:103], v[102:103], v[192:193] neg_lo:[0,1] neg_hi:[0,1]
	v_exp_f32_e32 v203, v87
	v_add_f32_e32 v87, v102, v103
	v_mov_b32_e32 v102, v101
	v_mov_b32_e32 v177, v161
	v_pk_add_f32 v[102:103], v[102:103], v[176:177] neg_lo:[0,1] neg_hi:[0,1]
	v_exp_f32_e32 v192, v87
	v_add_f32_e32 v87, v102, v103
	v_mov_b32_e32 v101, v103
	v_mov_b32_e32 v102, v160
	v_mov_b32_e32 v103, v176
	v_pk_add_f32 v[100:101], v[100:101], v[102:103] neg_lo:[0,1] neg_hi:[0,1]
	v_exp_f32_e32 v177, v87
	v_add_f32_e32 v87, v100, v101
	v_mov_b32_e32 v100, v99
	v_pk_mov_b32 v[102:103], v[158:159], v[160:161] op_sel:[1,0]
	v_exp_f32_e32 v176, v87
	v_pk_add_f32 v[100:101], v[100:101], v[102:103] neg_lo:[0,1] neg_hi:[0,1]
	v_mov_b32_e32 v246, v241
	v_add_f32_e32 v87, v100, v101
	v_mov_b32_e32 v99, v101
	v_mov_b32_e32 v100, v15
	v_mov_b32_e32 v101, v159
	v_pk_add_f32 v[98:99], v[98:99], v[100:101] neg_lo:[0,1] neg_hi:[0,1]
	v_exp_f32_e32 v102, v87
	v_add_f32_e32 v87, v98, v99
	v_mov_b32_e32 v98, v97
	v_mov_b32_e32 v159, v15
	v_pk_add_f32 v[98:99], v[98:99], v[158:159] neg_lo:[0,1] neg_hi:[0,1]
	v_exp_f32_e32 v100, v87
	v_add_f32_e32 v15, v98, v99
	v_exp_f32_e32 v98, v15
	v_mov_b32_e32 v97, v99
	v_mov_b32_e32 v15, v158
	v_pk_add_f32 v[14:15], v[96:97], v[14:15] neg_lo:[0,1] neg_hi:[0,1]
	v_pk_add_f32 v[96:97], v[238:239], v[244:245]
	v_add_f32_e32 v14, v14, v15
	v_exp_f32_e32 v99, v14
	v_pk_add_f32 v[14:15], v[190:191], v[196:197]
	v_mov_b32_e32 v101, v97
	v_mov_b32_e32 v87, v15
	v_mov_b32_e32 v95, v15
	s_nop 1
	v_permlane32_swap_b32_e32 v87, v95
	v_cndmask_b32_e64 v87, v87, v95, s[8:9]
	v_mov_b32_e32 v95, v97
	s_nop 1
	v_permlane32_swap_b32_e32 v95, v101
	v_cndmask_b32_e64 v101, v95, v101, s[8:9]
	v_pk_add_f32 v[14:15], v[14:15], v[96:97]
	v_add_f32_e32 v157, v87, v101
	v_cndmask_b32_e64 v95, 0, v101, s[8:9]
	v_pk_add_f32 v[14:15], v[156:157], v[14:15]
	v_mov_b32_e32 v247, v243
	v_add_f32_e32 v95, v14, v95
	v_add_f32_e32 v96, v252, v95
	v_pk_add_f32 v[94:95], v[94:95], v[246:247] neg_lo:[0,1] neg_hi:[0,1]
	v_mov_b32_e32 v243, v241
	v_add_f32_e32 v94, v94, v95
	v_exp_f32_e32 v103, v94
	v_mov_b32_e32 v94, v93
	v_pk_add_f32 v[94:95], v[94:95], v[242:243] neg_lo:[0,1] neg_hi:[0,1]
	v_mov_b32_e32 v248, v240
	v_add_f32_e32 v93, v94, v95
	v_mov_b32_e32 v249, v242
	v_exp_f32_e32 v94, v93
	v_mov_b32_e32 v93, v95
	v_pk_add_f32 v[92:93], v[92:93], v[248:249] neg_lo:[0,1] neg_hi:[0,1]
	v_pk_mov_b32 v[240:241], v[180:181], v[240:241] op_sel:[1,0]
	v_add_f32_e32 v92, v92, v93
	v_exp_f32_e32 v95, v92
	v_mov_b32_e32 v92, v91
; __device__ __forceinline__ float exp2_(float x) { return __builtin_amdgcn_exp2f(x); }
; #define AT_RV(vf, mb) do { vf[0] = *(const LAS bf16x8*)(lds + vb + (mb) * 4096); vf[1] = *(const LAS bf16x8*)(lds + (vb ^ 32u) + (mb) * 4096); \
;                 vf[2] = *(const LAS bf16x8*)(lds + (vb ^ 64u) + (mb) * 4096); vf[3] = *(const LAS bf16x8*)(lds + (vb ^ 96u) + (mb) * 4096); } while (0)
; #define AT_PV(o, vf) do { __builtin_amdgcn_s_setprio(1); o = MFMA32(vf[0], p00, o); o = MFMA32(vf[1], p01, o); o = MFMA32(vf[2], p10, o); o = MFMA32(vf[3], p11, o); __builtin_amdgcn_s_setprio(0); } while (0)
; __device__ __forceinline__ void sb_sub(f32x16& s, float& carry, const int hh) {
;     ...
;     for (int i = 15; i >= 8; --i) { const float wi = w[i]; s[i] = exp2_((s[i] + wi) + a); a += wi; }
;     a = carry + GB + GBp + (hh == 0 ? GAp : 0.f);
; #pragma unroll
;     for (int i = 7; i >= 0; --i) { const float wi = w[i]; s[i] = exp2_((s[i] + wi) + a); a += wi; }
;     carry += (GA + GB) + (GAp + GBp);
; template <int TYPE  >
; __device__ __forceinline__ void attn_item(const Params& P, const int b, const int h, const int qt, LAS unsigned char* lds) {
;     ...
;             const bf16x8 p00 = pack8(s0, 0), p01 = pack8(s0, 1), p10 = pack8(s1, 0), p11 = pack8(s1, 1);
;     ...
;             __builtin_amdgcn_sched_barrier(0);
;             AT_RV(vf1, 1); AT_PV(o0, vf0); __builtin_amdgcn_sched_barrier(0);
;             AT_RV(vf2, 2); AT_PV(o1, vf1); __builtin_amdgcn_sched_barrier(0);
;             AT_RV(vf3, 3); AT_PV(o2, vf2); __builtin_amdgcn_sched_barrier(0);
;             AT_PV(o3, vf3); __builtin_amdgcn_sched_barrier(0);
	v_pk_add_f32 v[92:93], v[92:93], v[240:241] neg_lo:[0,1] neg_hi:[0,1]
	v_mov_b32_e32 v250, v179
	v_add_f32_e32 v91, v92, v93
	v_mov_b32_e32 v251, v181
	v_exp_f32_e32 v92, v91
	v_mov_b32_e32 v91, v93
	v_pk_add_f32 v[90:91], v[90:91], v[250:251] neg_lo:[0,1] neg_hi:[0,1]
	v_mov_b32_e32 v181, v179
	v_add_f32_e32 v90, v90, v91
	v_exp_f32_e32 v93, v90
	v_mov_b32_e32 v90, v89
	v_pk_add_f32 v[90:91], v[90:91], v[180:181] neg_lo:[0,1] neg_hi:[0,1]
	v_mov_b32_e32 v179, v180
	v_add_f32_e32 v89, v90, v91
	v_exp_f32_e32 v90, v89
	v_mov_b32_e32 v89, v91
	v_pk_add_f32 v[88:89], v[88:89], v[178:179] neg_lo:[0,1] neg_hi:[0,1]
	v_cndmask_b32_e64 v87, 0, v87, s[8:9]
	v_add_f32_e32 v88, v88, v89
	v_add_f32_e32 v89, v14, v97
	v_add_f32_e32 v89, v89, v101
	v_add_f32_e32 v87, v87, v89
	v_add_f32_e32 v89, v236, v87
	v_pk_add_f32 v[86:87], v[86:87], v[234:235] neg_lo:[0,1] neg_hi:[0,1]
	v_pk_mov_b32 v[104:105], v[230:231], v[234:235] op_sel:[1,0]
	v_add_f32_e32 v86, v86, v87
	v_exp_f32_e32 v91, v86
	v_mov_b32_e32 v86, v85
	v_pk_add_f32 v[86:87], v[86:87], v[104:105] neg_lo:[0,1] neg_hi:[0,1]
	v_pk_mov_b32 v[108:109], v[106:107], v[230:231] op_sel:[1,0]
	v_add_f32_e32 v85, v86, v87
	v_exp_f32_e32 v86, v85
	v_mov_b32_e32 v85, v87
	v_pk_add_f32 v[84:85], v[84:85], v[230:231] neg_lo:[0,1] neg_hi:[0,1]
	v_exp_f32_e32 v96, v96
	v_add_f32_e32 v87, v84, v85
	v_mov_b32_e32 v84, v83
	v_pk_add_f32 v[84:85], v[84:85], v[108:109] neg_lo:[0,1] neg_hi:[0,1]
	v_exp_f32_e32 v88, v88
	v_add_f32_e32 v83, v84, v85
	v_exp_f32_e32 v97, v83
	v_mov_b32_e32 v83, v85
	v_pk_add_f32 v[82:83], v[82:83], v[106:107] neg_lo:[0,1] neg_hi:[0,1]
	v_pk_mov_b32 v[84:85], v[110:111], v[106:107] op_sel:[1,0]
	v_add_f32_e32 v101, v82, v83
	v_mov_b32_e32 v82, v81
	v_pk_add_f32 v[82:83], v[82:83], v[84:85] neg_lo:[0,1] neg_hi:[0,1]
	v_exp_f32_e32 v89, v89
	v_add_f32_e32 v81, v82, v83
	v_exp_f32_e32 v82, v81
	v_mov_b32_e32 v81, v83
	v_pk_add_f32 v[80:81], v[80:81], v[110:111] neg_lo:[0,1] neg_hi:[0,1]
	v_exp_f32_e32 v83, v87
	v_add_f32_e32 v80, v80, v81
	v_exp_f32_e32 v80, v80
	v_exp_f32_e32 v81, v101
	v_add_f32_e32 v156, v14, v15
	v_cvt_pk_bf16_f32 v84, v88, v90
	v_cvt_pk_bf16_f32 v80, v80, v82
	v_cvt_pk_bf16_f32 v81, v81, v97
	v_cvt_pk_bf16_f32 v82, v83, v86
	v_cvt_pk_bf16_f32 v83, v91, v89
	v_cvt_pk_bf16_f32 v85, v93, v92
	v_cvt_pk_bf16_f32 v86, v95, v94
	v_cvt_pk_bf16_f32 v87, v103, v96
	v_cvt_pk_bf16_f32 v88, v99, v98
	v_cvt_pk_bf16_f32 v89, v100, v102
	v_cvt_pk_bf16_f32 v90, v176, v177
	v_cvt_pk_bf16_f32 v91, v192, v203
	v_cvt_pk_bf16_f32 v92, v194, v195
	v_cvt_pk_bf16_f32 v93, v199, v198
	v_cvt_pk_bf16_f32 v94, v200, v201
	v_cvt_pk_bf16_f32 v95, v202, v232
	ds_read_b128 v[96:99], v0 offset:20480
	ds_read_b128 v[100:103], v187 offset:4096
	ds_read_b128 v[104:107], v188 offset:4096
	ds_read_b128 v[108:111], v189 offset:4096
	s_setprio 1
	s_waitcnt lgkmcnt(0)
	v_mfma_f32_32x32x16_bf16 v[64:79], v[6:9], v[80:83], v[64:79]
	v_mfma_f32_32x32x16_bf16 v[64:79], v[2:5], v[84:87], v[64:79]
	v_mfma_f32_32x32x16_bf16 v[64:79], v[144:147], v[88:91], v[64:79]
	v_mfma_f32_32x32x16_bf16 v[64:79], v[10:13], v[92:95], v[64:79]
	s_setprio 0
	ds_read_b128 v[2:5], v0 offset:24576
	ds_read_b128 v[6:9], v187 offset:8192
	ds_read_b128 v[10:13], v188 offset:8192
	ds_read_b128 v[144:147], v189 offset:8192
	s_setprio 1
	v_mfma_f32_32x32x16_bf16 v[48:63], v[96:99], v[80:83], v[48:63]
	v_mfma_f32_32x32x16_bf16 v[48:63], v[100:103], v[84:87], v[48:63]
	v_mfma_f32_32x32x16_bf16 v[48:63], v[104:107], v[88:91], v[48:63]
	v_mfma_f32_32x32x16_bf16 v[48:63], v[108:111], v[92:95], v[48:63]
	s_setprio 0
	ds_read_b128 v[96:99], v0 offset:28672
	ds_read_b128 v[100:103], v187 offset:12288
	ds_read_b128 v[104:107], v188 offset:12288
	ds_read_b128 v[108:111], v189 offset:12288
	s_setprio 1
	s_waitcnt lgkmcnt(0)
	v_mfma_f32_32x32x16_bf16 v[32:47], v[2:5], v[80:83], v[32:47]
	v_mfma_f32_32x32x16_bf16 v[32:47], v[6:9], v[84:87], v[32:47]
	v_mfma_f32_32x32x16_bf16 v[32:47], v[10:13], v[88:91], v[32:47]
	v_mfma_f32_32x32x16_bf16 v[32:47], v[144:147], v[92:95], v[32:47]
	s_setprio 0
	s_setprio 1
	v_mfma_f32_32x32x16_bf16 v[16:31], v[96:99], v[80:83], v[16:31]
	v_mfma_f32_32x32x16_bf16 v[16:31], v[100:103], v[84:87], v[16:31]
	v_mfma_f32_32x32x16_bf16 v[16:31], v[104:107], v[88:91], v[16:31]
	v_mfma_f32_32x32x16_bf16 v[16:31], v[108:111], v[92:95], v[16:31]
	s_setprio 0
	s_and_b64 vcc, exec, s[14:15]
	s_cbranch_vccnz .LBB0_1101
